# attention: K and V fragment LDS reads feeding the QK / PV MFMAs software-pipelined 5 reads ahead through a rolling pool of 6 spare VGPR quads (v230-v253), counted lgkmcnt waits recomputed
# speedup vs baseline: 1.0013x; 1.0013x over previous
.LBB0_317:
	v_or_b32_e32 v0, s84, v124
	v_mad_u64_u32 v[8:9], s[74:75], v0, s92, v[140:141]
	ds_read_b128 v[230:233], v8
	ds_read_b128 v[234:237], v8 offset:32
	ds_read_b128 v[238:241], v8 offset:64
	ds_read_b128 v[242:245], v8 offset:96
	ds_read_b128 v[246:249], v153
	ds_read_b128 v[250:253], v153 offset:32
	v_or_b32_e32 v126, s84, v145
	v_lshl_add_u64 v[166:167], s[66:67], 0, v[126:127]
	s_waitcnt lgkmcnt(5)
	v_mfma_f32_32x32x16_bf16 v[64:79], v[230:233], v[48:51], 0
	ds_read_b128 v[230:233], v153 offset:64
	v_mov_b64_e32 v[190:191], s[50:51]
	v_mov_b32_e32 v161, v127
	s_waitcnt lgkmcnt(5)
	v_mfma_f32_32x32x16_bf16 v[64:79], v[234:237], v[108:111], v[64:79]
	ds_read_b128 v[234:237], v153 offset:96
	v_mad_u64_u32 v[8:9], s[74:75], v166, s95, v[190:191]
	v_mad_i32_i24 v9, v167, s95, v9
	s_waitcnt lgkmcnt(5)
	v_mfma_f32_32x32x16_bf16 v[64:79], v[238:241], v[104:107], v[64:79]
	ds_read_b128 v[238:241], v153 offset:4608
	s_waitcnt lgkmcnt(5)
	v_mfma_f32_32x32x16_bf16 v[64:79], v[242:245], v[120:123], v[64:79]
	ds_read_b128 v[242:245], v153 offset:4640
	s_waitcnt lgkmcnt(5)
	v_mfma_f32_32x32x16_bf16 v[32:47], v[246:249], v[48:51], 0
	ds_read_b128 v[246:249], v153 offset:4672
	s_waitcnt lgkmcnt(5)
	v_mfma_f32_32x32x16_bf16 v[32:47], v[250:253], v[108:111], v[32:47]
	ds_read_b128 v[250:253], v153 offset:4704
	s_waitcnt lgkmcnt(5)
	v_mfma_f32_32x32x16_bf16 v[32:47], v[230:233], v[104:107], v[32:47]
	ds_read_b128 v[230:233], v153 offset:9216
	s_waitcnt lgkmcnt(5)
	v_mfma_f32_32x32x16_bf16 v[32:47], v[234:237], v[120:123], v[32:47]
	ds_read_b128 v[234:237], v153 offset:9248
	s_waitcnt lgkmcnt(5)
	v_mfma_f32_32x32x16_bf16 v[16:31], v[238:241], v[48:51], 0
	ds_read_b128 v[238:241], v153 offset:9280
	s_waitcnt lgkmcnt(5)
	v_mfma_f32_32x32x16_bf16 v[16:31], v[242:245], v[108:111], v[16:31]
	ds_read_b128 v[242:245], v153 offset:9312
	s_waitcnt lgkmcnt(5)
	v_mfma_f32_32x32x16_bf16 v[16:31], v[246:249], v[104:107], v[16:31]
	ds_read_b128 v[246:249], v153 offset:13824
	v_lshl_add_u64 v[0:1], v[8:9], 0, s[70:71]
	v_lshl_add_u64 v[8:9], v[0:1], 0, v[160:161]
	v_add_co_u32_e32 v60, vcc, s96, v8
	s_nop 1
	v_addc_co_u32_e32 v61, vcc, 0, v9, vcc
	s_waitcnt lgkmcnt(5)
	v_mfma_f32_32x32x16_bf16 v[16:31], v[250:253], v[120:123], v[16:31]
	ds_read_b128 v[250:253], v153 offset:13856
	v_or_b32_e32 v4, 8, v126
	v_mov_b32_e32 v5, v127
	v_lshl_add_u64 v[56:57], s[66:67], 0, v[4:5]
	v_mad_u64_u32 v[58:59], s[74:75], v56, s95, v[190:191]
	v_mad_i32_i24 v59, v57, s95, v59
	v_lshl_add_u64 v[56:57], v[58:59], 0, s[70:71]
	s_waitcnt lgkmcnt(5)
	v_mfma_f32_32x32x16_bf16 v[0:15], v[230:233], v[48:51], 0
	ds_read_b128 v[230:233], v153 offset:13888
	v_lshl_add_u64 v[62:63], v[56:57], 0, v[160:161]
	v_add_co_u32_e32 v62, vcc, s96, v62
	s_nop 1
	v_addc_co_u32_e32 v63, vcc, 0, v63, vcc
	s_waitcnt lgkmcnt(5)
	v_mfma_f32_32x32x16_bf16 v[0:15], v[234:237], v[108:111], v[0:15]
	ds_read_b128 v[234:237], v153 offset:13920
	global_load_dwordx4 v[116:119], v[60:61], off nt
	global_load_dwordx4 v[112:115], v[62:63], off nt
	v_or_b32_e32 v60, 16, v126
	v_mov_b32_e32 v61, v127
	v_or_b32_e32 v126, 24, v126
	v_lshl_add_u64 v[202:203], s[66:67], 0, v[126:127]
	s_waitcnt lgkmcnt(5)
	v_mfma_f32_32x32x16_bf16 v[0:15], v[238:241], v[104:107], v[0:15]
	v_lshl_add_u64 v[56:57], s[66:67], 0, v[60:61]
	v_mad_u64_u32 v[58:59], s[74:75], v56, s95, v[190:191]
	v_mad_i32_i24 v59, v57, s95, v59
	v_lshl_add_u64 v[60:61], v[58:59], 0, s[70:71]
	v_mad_u64_u32 v[190:191], s[74:75], v202, s95, v[190:191]
	s_waitcnt lgkmcnt(4)
	v_mfma_f32_32x32x16_bf16 v[0:15], v[242:245], v[120:123], v[0:15]
	v_lshl_add_u64 v[52:53], v[60:61], 0, v[160:161]
	v_add_co_u32_e32 v206, vcc, s96, v52
	v_mad_i32_i24 v191, v203, s95, v191
	s_nop 0
	v_addc_co_u32_e32 v207, vcc, 0, v53, vcc
	s_waitcnt lgkmcnt(3)
	v_mfma_f32_32x32x16_bf16 v[48:63], v[246:249], v[48:51], 0
	v_lshl_add_u64 v[190:191], v[190:191], 0, s[70:71]
	s_waitcnt lgkmcnt(2)
	v_mfma_f32_32x32x16_bf16 v[48:63], v[250:253], v[108:111], v[48:63]
	v_lshl_add_u64 v[108:109], v[190:191], 0, v[160:161]
	v_add_co_u32_e32 v190, vcc, s96, v108
	s_nop 0
	v_addc_co_u32_e32 v191, vcc, 0, v109, vcc
	s_andn2_b64 vcc, exec, s[72:73]
	s_waitcnt lgkmcnt(1)
	v_mfma_f32_32x32x16_bf16 v[48:63], v[230:233], v[104:107], v[48:63]
	global_load_dwordx4 v[108:111], v[206:207], off nt
	global_load_dwordx4 v[104:107], v[190:191], off nt
	s_waitcnt lgkmcnt(0)
	v_mfma_f32_32x32x16_bf16 v[48:63], v[234:237], v[120:123], v[48:63]
	s_cbranch_vccz .LBB0_319
	v_cndmask_b32_e64 v120, v188, v64, s[8:9]
	v_cndmask_b32_e64 v189, v65, v188, s[10:11]
	v_cndmask_b32_e64 v161, v188, v66, s[12:13]
	v_cndmask_b32_e64 v159, v188, v67, s[14:15]
	v_cndmask_b32_e64 v157, v188, v68, s[16:17]
	v_cndmask_b32_e64 v126, v188, v69, s[18:19]
	v_cndmask_b32_e64 v123, v188, v70, s[20:21]
	v_cndmask_b32_e64 v122, v188, v71, s[22:23]
	v_cndmask_b32_e64 v121, v188, v72, s[24:25]
	v_cndmask_b32_e64 v73, v188, v73, s[26:27]
	v_cndmask_b32_e64 v72, v188, v74, s[28:29]
	v_cndmask_b32_e64 v71, v188, v75, s[30:31]
	v_cndmask_b32_e64 v70, v188, v76, s[34:35]
	v_cndmask_b32_e64 v69, v188, v77, s[36:37]
	v_cndmask_b32_e64 v68, v188, v78, s[38:39]
	v_cndmask_b32_e64 v67, v188, v79, s[40:41]
	s_branch .LBB0_320

.LBB0_320:
	v_cndmask_b32_e64 v74, v188, v49, s[10:11]
	v_max3_f32 v49, v120, s97, v189
	v_max3_f32 v49, v49, v161, v159
	v_max3_f32 v49, v49, v157, v126
	v_max3_f32 v49, v49, v123, v122
	v_max3_f32 v49, v49, v121, v73
	v_max3_f32 v49, v49, v72, v71
	v_max3_f32 v49, v49, v70, v69
	v_max3_f32 v49, v49, v68, v67
	v_max3_f32 v49, v49, v32, v33
	v_max3_f32 v49, v49, v34, v35
	v_max3_f32 v49, v49, v36, v37
	v_max3_f32 v49, v49, v38, v39
	v_max3_f32 v49, v49, v40, v41
	v_max3_f32 v49, v49, v42, v43
	v_max3_f32 v49, v49, v44, v45
	v_max3_f32 v49, v49, v46, v47
	v_max3_f32 v49, v49, v16, v17
	v_max3_f32 v49, v49, v18, v19
	v_max3_f32 v49, v49, v20, v21
	v_max3_f32 v49, v49, v22, v23
	v_max3_f32 v49, v49, v24, v25
	v_max3_f32 v49, v49, v26, v27
	v_max3_f32 v49, v49, v28, v29
	v_max3_f32 v49, v49, v30, v31
	v_max3_f32 v49, v49, v0, v1
	v_max3_f32 v49, v49, v2, v3
	v_max3_f32 v49, v49, v4, v5
	v_max3_f32 v49, v49, v6, v7
	v_max3_f32 v49, v49, v8, v9
	v_max3_f32 v49, v49, v10, v11
	v_cndmask_b32_e64 v64, v48, v188, s[8:9]
	v_max3_f32 v49, v49, v12, v13
	v_cndmask_b32_e64 v75, v64, v48, s[10:11]
	v_max3_f32 v49, v49, v14, v15
	v_cndmask_b32_e64 v76, v50, v188, s[12:13]
	v_cndmask_b32_e64 v77, v51, v188, s[14:15]
	v_max3_f32 v49, v49, v75, v74
	v_cndmask_b32_e64 v78, v52, v188, s[16:17]
	v_cndmask_b32_e64 v66, v53, v188, s[18:19]
	v_max3_f32 v49, v49, v76, v77
	v_cndmask_b32_e64 v65, v54, v188, s[20:21]
	v_cndmask_b32_e64 v64, v55, v188, s[22:23]
	v_max3_f32 v49, v49, v78, v66
	v_cndmask_b32_e64 v56, v56, v188, s[24:25]
	v_cndmask_b32_e64 v55, v57, v188, s[26:27]
	v_max3_f32 v49, v49, v65, v64
	v_cndmask_b32_e64 v54, v58, v188, s[28:29]
	v_cndmask_b32_e64 v53, v59, v188, s[30:31]
	v_max3_f32 v49, v49, v56, v55
	v_cndmask_b32_e64 v52, v60, v188, s[34:35]
	v_cndmask_b32_e64 v51, v61, v188, s[36:37]
	v_max3_f32 v49, v49, v54, v53
	v_cndmask_b32_e64 v50, v62, v188, s[38:39]
	v_cndmask_b32_e64 v48, v63, v188, s[40:41]
	v_max3_f32 v49, v49, v52, v51
	v_max3_f32 v49, v49, v50, v48
	ds_bpermute_b32 v57, v171, v49
	v_add_u32_e32 v228, s69, v175
	s_waitcnt lgkmcnt(0)
	v_max_f32_e32 v57, v57, v57
	v_max_f32_e32 v49, v49, v57
	v_sub_f32_e32 v57, v120, v49
	v_exp_f32_e32 v57, v57
	v_sub_f32_e32 v58, v189, v49
	v_exp_f32_e32 v58, v58
	v_sub_f32_e32 v59, v161, v49
	v_exp_f32_e32 v59, v59
	v_sub_f32_e32 v61, v159, v49
	v_exp_f32_e32 v61, v61
	v_sub_f32_e32 v62, v157, v49
	v_add_f32_e32 v60, 0, v57
	v_exp_f32_e32 v62, v62
	v_sub_f32_e32 v63, v126, v49
	v_add_f32_e32 v60, v58, v60
	v_exp_f32_e32 v63, v63
	v_sub_f32_e32 v79, v123, v49
	v_add_f32_e32 v60, v59, v60
	v_exp_f32_e32 v79, v79
	v_sub_f32_e32 v120, v122, v49
	v_add_f32_e32 v60, v61, v60
	v_exp_f32_e32 v120, v120
	v_sub_f32_e32 v121, v121, v49
	v_add_f32_e32 v60, v62, v60
	v_exp_f32_e32 v121, v121
	v_sub_f32_e32 v73, v73, v49
	v_add_f32_e32 v60, v63, v60
	v_exp_f32_e32 v73, v73
	v_sub_f32_e32 v72, v72, v49
	v_add_f32_e32 v60, v79, v60
	v_exp_f32_e32 v72, v72
	v_sub_f32_e32 v71, v71, v49
	v_add_f32_e32 v60, v120, v60
	v_exp_f32_e32 v71, v71
	v_sub_f32_e32 v70, v70, v49
	v_add_f32_e32 v60, v121, v60
	v_exp_f32_e32 v70, v70
	v_sub_f32_e32 v69, v69, v49
	v_add_f32_e32 v60, v73, v60
	v_exp_f32_e32 v69, v69
	v_sub_f32_e32 v68, v68, v49
	v_add_f32_e32 v60, v72, v60
	v_exp_f32_e32 v68, v68
	v_sub_f32_e32 v67, v67, v49
	v_add_f32_e32 v60, v71, v60
	v_exp_f32_e32 v67, v67
	v_sub_f32_e32 v32, v32, v49
	v_add_f32_e32 v60, v70, v60
	v_exp_f32_e32 v122, v32
	v_sub_f32_e32 v32, v33, v49
	v_add_f32_e32 v60, v69, v60
	v_exp_f32_e32 v123, v32
	v_sub_f32_e32 v32, v34, v49
	v_add_f32_e32 v60, v68, v60
	v_exp_f32_e32 v126, v32
	v_sub_f32_e32 v33, v35, v49
	v_add_f32_e32 v32, v67, v60
	v_exp_f32_e32 v60, v33
	v_sub_f32_e32 v33, v36, v49
	v_add_f32_e32 v32, v122, v32
	v_exp_f32_e32 v157, v33
	v_sub_f32_e32 v33, v37, v49
	v_add_f32_e32 v32, v123, v32
	v_exp_f32_e32 v159, v33
	v_sub_f32_e32 v33, v38, v49
	v_add_f32_e32 v32, v126, v32
	v_exp_f32_e32 v161, v33
	v_sub_f32_e32 v33, v39, v49
	v_add_f32_e32 v32, v60, v32
	v_exp_f32_e32 v189, v33
	v_sub_f32_e32 v33, v40, v49
	v_add_f32_e32 v32, v157, v32
	v_exp_f32_e32 v190, v33
	v_sub_f32_e32 v33, v41, v49
	v_add_f32_e32 v32, v159, v32
	v_exp_f32_e32 v191, v33
	v_sub_f32_e32 v33, v42, v49
	v_add_f32_e32 v32, v161, v32
	v_exp_f32_e32 v192, v33
	v_sub_f32_e32 v33, v43, v49
	v_add_f32_e32 v32, v189, v32
	v_exp_f32_e32 v198, v33
	v_sub_f32_e32 v33, v44, v49
	v_add_f32_e32 v32, v190, v32
	v_exp_f32_e32 v199, v33
	v_sub_f32_e32 v33, v45, v49
	v_add_f32_e32 v32, v191, v32
	v_exp_f32_e32 v200, v33
	v_sub_f32_e32 v33, v46, v49
	v_add_f32_e32 v32, v192, v32
	v_exp_f32_e32 v201, v33
	v_sub_f32_e32 v33, v47, v49
	v_add_f32_e32 v32, v198, v32
	v_exp_f32_e32 v202, v33
	v_sub_f32_e32 v16, v16, v49
	v_add_f32_e32 v32, v199, v32
	v_exp_f32_e32 v203, v16
	v_sub_f32_e32 v16, v17, v49
	v_add_f32_e32 v32, v200, v32
	v_exp_f32_e32 v204, v16
	v_sub_f32_e32 v16, v18, v49
	v_add_f32_e32 v32, v201, v32
	v_exp_f32_e32 v205, v16
	v_sub_f32_e32 v17, v19, v49
	v_add_f32_e32 v16, v202, v32
	v_exp_f32_e32 v206, v17
	v_sub_f32_e32 v17, v20, v49
	v_add_f32_e32 v16, v203, v16
	v_exp_f32_e32 v207, v17
	v_sub_f32_e32 v17, v21, v49
	v_add_f32_e32 v16, v204, v16
	v_exp_f32_e32 v208, v17
	v_sub_f32_e32 v17, v22, v49
	v_add_f32_e32 v16, v205, v16
	v_exp_f32_e32 v209, v17
	v_sub_f32_e32 v17, v23, v49
	v_add_f32_e32 v16, v206, v16
	v_exp_f32_e32 v210, v17
	v_sub_f32_e32 v17, v24, v49
	v_add_f32_e32 v16, v207, v16
	v_exp_f32_e32 v211, v17
	v_sub_f32_e32 v17, v25, v49
	v_add_f32_e32 v16, v208, v16
	v_exp_f32_e32 v212, v17
	v_sub_f32_e32 v17, v26, v49
	v_add_f32_e32 v16, v209, v16
	v_exp_f32_e32 v213, v17
	v_sub_f32_e32 v17, v27, v49
	v_add_f32_e32 v16, v210, v16
	v_exp_f32_e32 v214, v17
	v_sub_f32_e32 v17, v28, v49
	v_add_f32_e32 v16, v211, v16
	v_exp_f32_e32 v215, v17
	v_sub_f32_e32 v17, v29, v49
	v_add_f32_e32 v16, v212, v16
	v_exp_f32_e32 v216, v17
	v_sub_f32_e32 v17, v30, v49
	v_add_f32_e32 v16, v213, v16
	v_exp_f32_e32 v217, v17
	v_sub_f32_e32 v17, v31, v49
	v_add_f32_e32 v16, v214, v16
	v_exp_f32_e32 v218, v17
	v_sub_f32_e32 v0, v0, v49
	v_add_f32_e32 v16, v215, v16
	v_exp_f32_e32 v219, v0
	v_sub_f32_e32 v0, v1, v49
	v_add_f32_e32 v16, v216, v16
	v_exp_f32_e32 v220, v0
	v_sub_f32_e32 v0, v2, v49
	v_add_f32_e32 v16, v217, v16
	v_exp_f32_e32 v221, v0
	v_sub_f32_e32 v1, v3, v49
	v_add_f32_e32 v0, v218, v16
	v_exp_f32_e32 v222, v1
	v_sub_f32_e32 v1, v4, v49
	v_add_f32_e32 v0, v219, v0
	v_exp_f32_e32 v223, v1
	v_sub_f32_e32 v1, v5, v49
	v_add_f32_e32 v0, v220, v0
	v_exp_f32_e32 v224, v1
	v_sub_f32_e32 v1, v6, v49
	v_add_f32_e32 v0, v221, v0
	v_exp_f32_e32 v225, v1
	v_add_f32_e32 v0, v222, v0
	v_add_f32_e32 v0, v223, v0
	v_add_f32_e32 v0, v224, v0
	v_add_f32_e32 v4, v225, v0
	v_sub_f32_e32 v0, v7, v49
	v_exp_f32_e32 v226, v0
	v_sub_f32_e32 v0, v8, v49
	v_exp_f32_e32 v227, v0
	v_add_f32_e32 v4, v226, v4
	v_cvt_pk_bf16_f32 v5, v59, v61
	v_add_f32_e32 v229, v227, v4
	v_cvt_pk_bf16_f32 v4, v57, v58
	v_cvt_pk_bf16_f32 v6, v62, v63
	v_cvt_pk_bf16_f32 v7, v79, v120
	v_add_u32_e32 v57, s69, v174
	ds_read2_b64 v[230:233], v228 offset1:2
	ds_read2_b64 v[234:237], v57 offset1:2
	ds_read2_b64 v[238:241], v228 offset0:4 offset1:6
	ds_read2_b64 v[242:245], v57 offset0:4 offset1:6
	ds_read2_b64 v[246:249], v228 offset0:8 offset1:10
	ds_read2_b64 v[250:253], v57 offset0:8 offset1:10
	s_waitcnt lgkmcnt(5)
	v_mfma_f32_32x32x16_bf16 v[32:47], v[230:233], v[4:7], 0
	ds_read2_b64 v[230:233], v228 offset0:12 offset1:14
	v_sub_f32_e32 v0, v9, v49
	v_exp_f32_e32 v58, v0
	v_sub_f32_e32 v0, v10, v49
	v_exp_f32_e32 v59, v0
	v_sub_f32_e32 v0, v11, v49
	v_exp_f32_e32 v61, v0
	s_waitcnt lgkmcnt(5)
	v_mfma_f32_32x32x16_bf16 v[16:31], v[234:237], v[4:7], 0
	ds_read2_b64 v[234:237], v57 offset0:12 offset1:14
	v_sub_f32_e32 v4, v12, v49
	v_exp_f32_e32 v12, v4
	v_cvt_pk_bf16_f32 v8, v121, v73
	v_cvt_pk_bf16_f32 v9, v72, v71
	v_cvt_pk_bf16_f32 v10, v70, v69
	v_cvt_pk_bf16_f32 v11, v68, v67
	v_sub_f32_e32 v48, v48, v49
	s_waitcnt lgkmcnt(5)
	v_mfma_f32_32x32x16_bf16 v[32:47], v[238:241], v[8:11], v[32:47]
	ds_read2_b64 v[238:241], v228 offset0:16 offset1:18
	v_add_f32_e32 v0, v58, v229
	v_add_f32_e32 v0, v59, v0
	v_add_f32_e32 v0, v61, v0
	v_add_f32_e32 v62, v12, v0
	v_sub_f32_e32 v0, v13, v49
	v_exp_f32_e32 v13, v0
	s_waitcnt lgkmcnt(5)
	v_mfma_f32_32x32x16_bf16 v[16:31], v[242:245], v[8:11], v[16:31]
	ds_read2_b64 v[242:245], v57 offset0:16 offset1:18
	v_sub_f32_e32 v4, v14, v49
	v_exp_f32_e32 v14, v4
	v_cvt_pk_bf16_f32 v4, v122, v123
	v_cvt_pk_bf16_f32 v5, v126, v60
	v_cvt_pk_bf16_f32 v6, v157, v159
	v_cvt_pk_bf16_f32 v7, v161, v189
	v_exp_f32_e32 v48, v48
	s_waitcnt lgkmcnt(5)
	v_mfma_f32_32x32x16_bf16 v[32:47], v[246:249], v[4:7], v[32:47]
	ds_read2_b64 v[246:249], v228 offset0:20 offset1:22
	v_add_f32_e32 v0, v13, v62
	v_add_f32_e32 v60, v14, v0
	v_sub_f32_e32 v0, v15, v49
	v_exp_f32_e32 v15, v0
	v_sub_f32_e32 v0, v75, v49
	v_exp_f32_e32 v62, v0
	s_waitcnt lgkmcnt(5)
	v_mfma_f32_32x32x16_bf16 v[16:31], v[250:253], v[4:7], v[16:31]
	ds_read2_b64 v[250:253], v57 offset0:20 offset1:22
	v_add_f32_e32 v4, v15, v60
	v_add_f32_e32 v60, v62, v4
	v_cvt_pk_bf16_f32 v4, v190, v191
	v_cvt_pk_bf16_f32 v5, v192, v198
	v_cvt_pk_bf16_f32 v6, v199, v200
	v_cvt_pk_bf16_f32 v7, v201, v202
	s_waitcnt lgkmcnt(5)
	v_mfma_f32_32x32x16_bf16 v[32:47], v[230:233], v[4:7], v[32:47]
	ds_read2_b64 v[230:233], v228 offset0:24 offset1:26
	v_sub_f32_e32 v0, v74, v49
	v_exp_f32_e32 v63, v0
	v_sub_f32_e32 v0, v76, v49
	v_exp_f32_e32 v67, v0
	v_sub_f32_e32 v0, v77, v49
	v_exp_f32_e32 v68, v0
	s_waitcnt lgkmcnt(5)
	v_mfma_f32_32x32x16_bf16 v[16:31], v[234:237], v[4:7], v[16:31]
	ds_read2_b64 v[234:237], v57 offset0:24 offset1:26
	v_sub_f32_e32 v4, v78, v49
	v_exp_f32_e32 v69, v4
	v_cvt_pk_bf16_f32 v4, v203, v204
	v_cvt_pk_bf16_f32 v5, v205, v206
	v_cvt_pk_bf16_f32 v6, v207, v208
	v_cvt_pk_bf16_f32 v7, v209, v210
	s_waitcnt lgkmcnt(5)
	v_mfma_f32_32x32x16_bf16 v[32:47], v[238:241], v[4:7], v[32:47]
	ds_read2_b64 v[238:241], v228 offset0:28 offset1:30
	v_add_f32_e32 v0, v63, v60
	v_add_f32_e32 v0, v67, v0
	v_add_f32_e32 v0, v68, v0
	v_add_f32_e32 v60, v69, v0
	v_sub_f32_e32 v0, v66, v49
	v_exp_f32_e32 v66, v0
	s_waitcnt lgkmcnt(5)
	v_mfma_f32_32x32x16_bf16 v[16:31], v[242:245], v[4:7], v[16:31]
	ds_read2_b64 v[242:245], v57 offset0:28 offset1:30
	v_sub_f32_e32 v4, v65, v49
	v_exp_f32_e32 v65, v4
	v_cvt_pk_bf16_f32 v4, v211, v212
	v_cvt_pk_bf16_f32 v5, v213, v214
	v_cvt_pk_bf16_f32 v6, v215, v216
	v_cvt_pk_bf16_f32 v7, v217, v218
	s_waitcnt lgkmcnt(5)
	v_mfma_f32_32x32x16_bf16 v[32:47], v[246:249], v[4:7], v[32:47]
	ds_read2_b64 v[246:249], v228 offset0:32 offset1:34
	v_add_f32_e32 v0, v66, v60
	v_add_f32_e32 v60, v65, v0
	v_sub_f32_e32 v0, v64, v49
	v_exp_f32_e32 v64, v0
	v_sub_f32_e32 v0, v56, v49
	v_exp_f32_e32 v56, v0
	s_waitcnt lgkmcnt(5)
	v_mfma_f32_32x32x16_bf16 v[16:31], v[250:253], v[4:7], v[16:31]
	ds_read2_b64 v[250:253], v57 offset0:32 offset1:34
	v_sub_f32_e32 v4, v55, v49
	v_exp_f32_e32 v55, v4
	v_cvt_pk_bf16_f32 v4, v219, v220
	v_cvt_pk_bf16_f32 v5, v221, v222
	v_cvt_pk_bf16_f32 v6, v223, v224
	v_cvt_pk_bf16_f32 v7, v225, v226
	s_waitcnt lgkmcnt(5)
	v_mfma_f32_32x32x16_bf16 v[32:47], v[230:233], v[4:7], v[32:47]
	ds_read2_b64 v[230:233], v228 offset0:36 offset1:38
	v_sub_f32_e32 v0, v54, v49
	v_exp_f32_e32 v54, v0
	v_add_f32_e32 v0, v64, v60
	v_add_f32_e32 v0, v56, v0
	v_add_f32_e32 v0, v55, v0
	v_add_f32_e32 v60, v54, v0
	s_waitcnt lgkmcnt(5)
	v_mfma_f32_32x32x16_bf16 v[16:31], v[234:237], v[4:7], v[16:31]
	ds_read2_b64 v[234:237], v57 offset0:36 offset1:38
	v_sub_f32_e32 v4, v53, v49
	v_exp_f32_e32 v53, v4
	v_cvt_pk_bf16_f32 v4, v227, v58
	v_cvt_pk_bf16_f32 v5, v59, v61
	v_cvt_pk_bf16_f32 v6, v12, v13
	v_cvt_pk_bf16_f32 v7, v14, v15
	v_sub_f32_e32 v15, v50, v49
	s_waitcnt lgkmcnt(5)
	v_mfma_f32_32x32x16_bf16 v[32:47], v[238:241], v[4:7], v[32:47]
	v_sub_f32_e32 v0, v52, v49
	v_exp_f32_e32 v13, v0
	v_sub_f32_e32 v0, v51, v49
	v_exp_f32_e32 v14, v0
	v_exp_f32_e32 v15, v15
	v_add_f32_e32 v12, v53, v60
	s_waitcnt lgkmcnt(4)
	v_mfma_f32_32x32x16_bf16 v[16:31], v[242:245], v[4:7], v[16:31]
	v_cvt_pk_bf16_f32 v4, v62, v63
	v_cvt_pk_bf16_f32 v5, v67, v68
	v_cvt_pk_bf16_f32 v6, v69, v66
	v_cvt_pk_bf16_f32 v7, v65, v64
	s_waitcnt lgkmcnt(3)
	v_mfma_f32_32x32x16_bf16 v[32:47], v[246:249], v[4:7], v[32:47]
	v_add_f32_e32 v0, v13, v12
	v_add_f32_e32 v0, v14, v0
	v_add_f32_e32 v0, v15, v0
	v_add_f32_e32 v12, v48, v0
	ds_bpermute_b32 v50, v171, v12
	s_waitcnt lgkmcnt(3)
	v_mfma_f32_32x32x16_bf16 v[16:31], v[250:253], v[4:7], v[16:31]
	v_sub_f32_e32 v4, v155, v49
	v_exp_f32_e32 v49, v4
	v_cvt_pk_bf16_f32 v4, v56, v55
	v_cvt_pk_bf16_f32 v5, v54, v53
	v_cvt_pk_bf16_f32 v6, v13, v14
	v_cvt_pk_bf16_f32 v7, v15, v48
	s_waitcnt lgkmcnt(2)
	v_mfma_f32_32x32x16_bf16 v[32:47], v[230:233], v[4:7], v[32:47]
	s_waitcnt lgkmcnt(0)
	v_add_f32_e32 v0, v12, v50
	v_add_f32_e32 v0, v49, v0
	v_div_scale_f32 v1, s[74:75], v0, v0, 1.0
	v_rcp_f32_e32 v2, v1
	s_nop 0
	v_fma_f32 v3, -v1, v2, 1.0
	v_fmac_f32_e32 v2, v3, v2
	v_div_scale_f32 v3, vcc, 1.0, v0, 1.0
	s_waitcnt lgkmcnt(1)
	v_mfma_f32_32x32x16_bf16 v[16:31], v[234:237], v[4:7], v[16:31]
	v_mul_f32_e32 v4, v3, v2
	v_fma_f32 v5, -v1, v4, v3
	v_fmac_f32_e32 v4, v5, v2
	v_fma_f32 v1, -v1, v4, v3
	v_div_fmas_f32 v1, v1, v2, v4
	v_div_fixup_f32 v48, v1, v0, 1.0
	v_pk_mul_f32 v[0:1], v[32:33], v[48:49] op_sel_hi:[1,0]
	v_pk_mul_f32 v[2:3], v[34:35], v[48:49] op_sel_hi:[1,0]
	v_pk_mul_f32 v[50:51], v[0:1], v[0:1]
	v_pk_mul_f32 v[34:35], v[2:3], v[2:3]
	v_pk_mul_f32 v[4:5], v[36:37], v[48:49] op_sel_hi:[1,0]
	v_pk_mul_f32 v[6:7], v[38:39], v[48:49] op_sel_hi:[1,0]
	v_pk_mul_f32 v[8:9], v[40:41], v[48:49] op_sel_hi:[1,0]
	v_pk_mul_f32 v[10:11], v[42:43], v[48:49] op_sel_hi:[1,0]
	v_pk_mul_f32 v[12:13], v[44:45], v[48:49] op_sel_hi:[1,0]
	v_pk_mul_f32 v[32:33], v[46:47], v[48:49] op_sel_hi:[1,0]
	v_pk_mul_f32 v[14:15], v[16:17], v[48:49] op_sel_hi:[1,0]
	v_pk_mul_f32 v[16:17], v[18:19], v[48:49] op_sel_hi:[1,0]
	v_pk_mul_f32 v[18:19], v[20:21], v[48:49] op_sel_hi:[1,0]
	v_pk_mul_f32 v[20:21], v[22:23], v[48:49] op_sel_hi:[1,0]
	v_pk_mul_f32 v[22:23], v[24:25], v[48:49] op_sel_hi:[1,0]
	v_pk_mul_f32 v[24:25], v[26:27], v[48:49] op_sel_hi:[1,0]
	v_pk_mul_f32 v[26:27], v[28:29], v[48:49] op_sel_hi:[1,0]
	v_pk_mul_f32 v[28:29], v[30:31], v[48:49] op_sel_hi:[1,0]
	v_add_f32_e32 v48, v50, v51
	v_add_f32_e32 v34, v34, v48
	v_pk_mul_f32 v[36:37], v[4:5], v[4:5]
	v_add_f32_e32 v34, v35, v34
	v_add_f32_e32 v34, v36, v34
	v_pk_mul_f32 v[38:39], v[6:7], v[6:7]
	v_add_f32_e32 v34, v37, v34
	v_add_f32_e32 v34, v38, v34
	v_pk_mul_f32 v[40:41], v[8:9], v[8:9]
	v_add_f32_e32 v34, v39, v34
	v_add_f32_e32 v34, v40, v34
	v_pk_mul_f32 v[42:43], v[10:11], v[10:11]
	v_add_f32_e32 v34, v41, v34
	v_add_f32_e32 v34, v42, v34
	v_pk_mul_f32 v[44:45], v[12:13], v[12:13]
	v_add_f32_e32 v34, v43, v34
	v_add_f32_e32 v34, v44, v34
	v_pk_mul_f32 v[46:47], v[32:33], v[32:33]
	v_add_f32_e32 v34, v45, v34
	v_add_f32_e32 v34, v46, v34
	v_pk_mul_f32 v[52:53], v[14:15], v[14:15]
	v_add_f32_e32 v34, v47, v34
	v_add_f32_e32 v34, v52, v34
	v_pk_mul_f32 v[54:55], v[16:17], v[16:17]
	v_add_f32_e32 v34, v53, v34
	v_add_f32_e32 v34, v54, v34
	v_pk_mul_f32 v[56:57], v[18:19], v[18:19]
	v_add_f32_e32 v34, v55, v34
	v_add_f32_e32 v34, v56, v34
	v_pk_mul_f32 v[58:59], v[20:21], v[20:21]
	v_add_f32_e32 v34, v57, v34
	v_add_f32_e32 v34, v58, v34
	v_pk_mul_f32 v[60:61], v[22:23], v[22:23]
	v_add_f32_e32 v34, v59, v34
	v_add_f32_e32 v34, v60, v34
	v_pk_mul_f32 v[62:63], v[24:25], v[24:25]
	v_add_f32_e32 v34, v61, v34
	v_add_f32_e32 v34, v62, v34
	v_pk_mul_f32 v[64:65], v[26:27], v[26:27]
	v_add_f32_e32 v34, v63, v34
	v_add_f32_e32 v34, v64, v34
	v_pk_mul_f32 v[30:31], v[28:29], v[28:29]
	v_add_f32_e32 v34, v65, v34
	v_add_f32_e32 v30, v30, v34
	v_add_f32_e32 v30, v31, v30
	ds_bpermute_b32 v31, v171, v30
	s_and_saveexec_b64 s[74:75], s[6:7]
	s_cbranch_execz .LBB0_314
	s_waitcnt lgkmcnt(0)
	v_add_f32_e32 v30, v30, v31
	ds_write_b32 v151, v30
	s_branch .LBB0_314

.LBB0_522:
	s_nop 0
	s_nop 0
	s_nop 0
	s_nop 0
	s_nop 0
	s_nop 0
	s_cmp_lt_i32 s80, 7
	s_cselect_b64 s[0:1], -1, 0
	s_cmp_gt_i32 s81, 6
	s_cselect_b64 s[4:5], -1, 0
	s_and_b64 s[0:1], s[0:1], s[4:5]
	s_andn2_b64 vcc, exec, s[0:1]
	s_cbranch_vccnz .LBB0_622
	v_lshrrev_b32_e32 v2, 1, v144
	v_lshrrev_b32_e32 v3, 5, v144
	v_and_b32_e32 v2, 24, v2
	v_and_b32_e32 v3, 4, v3
	v_bfe_u32 v4, v144, 2, 2
	v_lshlrev_b32_e32 v0, 4, v144
	v_and_b32_e32 v1, 32, v144
	v_bfe_u32 v10, v144, 2, 4
	v_or3_b32 v2, v3, v4, v2
	v_lshrrev_b32_e32 v3, 3, v144
	s_movk_i32 s0, 0x70
	v_bitop3_b32 v8, v0, v1, 48 bitop3:0x6c
	v_and_b32_e32 v9, 64, v144
	v_and_or_b32 v4, v3, s0, v10
	s_movk_i32 s0, 0x60
	v_add_u32_e32 v11, 0x2000, v0
	v_or_b32_e32 v1, v8, v9
	v_and_or_b32 v3, v3, s0, v2
	v_lshrrev_b32_e32 v0, 7, v11
	s_movk_i32 s0, 0xf0
	s_add_u32 s30, s62, 0x4000000
	v_lshl_or_b32 v150, v4, 12, v1
	v_and_or_b32 v3, v0, s0, v10
	s_movk_i32 s0, 0xe0
	s_addc_u32 s31, s63, 0
	v_and_or_b32 v0, v0, s0, v2
	s_lshl_b32 s0, s2, 2
	s_and_b32 s0, s0, 28
	s_ashr_i32 s1, s2, 6
	s_add_i32 s0, s0, s1
	s_waitcnt lgkmcnt(0)
	s_bfe_u32 s16, s2, 0x30003
	s_ashr_i32 s1, s0, 31
	s_lshl_b64 s[6:7], s[0:1], 20
	s_lshl_b32 s2, s16, 20
	s_add_u32 s1, s62, s2
	s_addc_u32 s3, s63, 0
	s_add_u32 s4, s1, 0x1200000
	s_addc_u32 s5, s3, 0
	s_add_u32 s8, s1, 0x1280000
	s_addc_u32 s9, s3, 0
	s_add_u32 s6, s30, s6
	s_addc_u32 s7, s31, s7
	s_add_u32 s10, s6, 0x80000
	v_readfirstlane_b32 s3, v144
	s_addc_u32 s11, s7, 0
	s_lshr_b32 s18, s3, 6
	s_lshl_b32 s1, s18, 10
	s_add_i32 s34, s1, 0
	s_add_i32 m0, s34, 0x10000
	v_lshl_or_b32 v154, v3, 12, v1
	global_load_lds_dwordx4 v150, s[4:5]
	s_add_i32 m0, s34, 0x12000
	v_lshl_or_b32 v148, v4, 12, v1
	global_load_lds_dwordx4 v154, s[4:5]
	s_add_i32 m0, s34, 0x14000
	s_add_i32 s35, s34, 0x2000
	global_load_lds_dwordx4 v150, s[8:9]
	s_add_i32 m0, s34, 0x16000
	v_lshl_or_b32 v152, v3, 12, v1
	global_load_lds_dwordx4 v154, s[8:9]
	s_mov_b32 m0, s34
	s_add_i32 s36, s34, 0x4000
	global_load_lds_dwordx4 v148, s[6:7]
	s_mov_b32 m0, s35
	s_add_i32 s37, s34, 0x6000
	global_load_lds_dwordx4 v152, s[6:7]
	s_mov_b32 m0, s36
	v_mov_b32_e32 v151, 0
	global_load_lds_dwordx4 v148, s[10:11]
	s_mov_b32 m0, s37
	s_lshr_b32 s19, s3, 8
	global_load_lds_dwordx4 v152, s[10:11]
	v_mov_b32_e32 v155, v151
	v_mov_b32_e32 v149, v151
	v_mov_b32_e32 v153, v151
	s_cmp_eq_u32 s19, 1
	s_mov_b32 s38, 0
	v_lshl_add_u64 v[0:1], s[4:5], 0, v[150:151]
	v_lshl_add_u64 v[2:3], s[4:5], 0, v[154:155]
	v_lshl_add_u64 v[4:5], s[6:7], 0, v[148:149]
	s_cselect_b64 s[8:9], -1, 0
	s_cmp_lg_u32 s19, 1
	v_lshl_add_u64 v[6:7], s[6:7], 0, v[152:153]
	s_cbranch_scc1 .LBB0_525
	s_barrier
